# SWA prompt q-tile: zero initialisers of wave-uniformly guarded tile blocks moved to an out-of-line skip path (88 VALU fewer on the executed path), on top of the canonicalise fold
# baseline (speedup 1.0000x reference)
; __device__ __forceinline__ void swa_prompt_unit(const Args& a, unsigned char* lds, int unit, int tid) {
;     ...
;         for (int t = 0; t < 16; ++t) { sc[t] = (f32x4){0.f, 0.f, 0.f, 0.f};
;             if (t >= t0 && t <= t0 + 8) {
; #pragma unroll
;                 for (int kk = 0; kk < 2; ++kk) { const bf16x8 af = *(const bf16x8*)(KL + (t * 16 + r16) * 144 + kk * 64 + q4 * 16); sc[t] = __builtin_amdgcn_mfma_f32_16x16x32_bf16(af, qf[kk], sc[t], 0, 0, 0); } } }
.LBB0_285:
	s_or_b64 exec, exec, s[0:1]
	v_cmp_gt_u32_e64 s[28:29], 2, v1
	s_and_saveexec_b64 s[0:1], s[28:29]
	s_cbranch_execz .Lz_1
	ds_read_b128 v[2:5], v187 offset:2304
	ds_read_b128 v[6:9], v187 offset:2368
	s_waitcnt lgkmcnt(1)
	v_mfma_f32_16x16x32_bf16 v[2:5], v[2:5], v[66:69], 0
	s_waitcnt lgkmcnt(0)
	v_mfma_f32_16x16x32_bf16 v[54:57], v[6:9], v[70:73], v[2:5]
.LBB0_287:
	s_or_b64 exec, exec, s[0:1]
	v_cmp_gt_u32_e64 s[42:43], 3, v1
	v_mov_b32_e32 v46, 0
	s_and_saveexec_b64 s[0:1], s[42:43]
	s_cbranch_execz .Lz_2
	ds_read_b128 v[2:5], v187 offset:4608
	ds_read_b128 v[6:9], v187 offset:4672
	s_waitcnt lgkmcnt(1)
	v_mfma_f32_16x16x32_bf16 v[2:5], v[2:5], v[66:69], 0
	s_waitcnt lgkmcnt(0)
	v_mfma_f32_16x16x32_bf16 v[58:61], v[6:9], v[70:73], v[2:5]
.LBB0_289:
	s_or_b64 exec, exec, s[0:1]
	v_cmp_gt_u32_e64 s[26:27], 4, v1
	s_and_saveexec_b64 s[0:1], s[26:27]
	s_cbranch_execz .Lz_3
	ds_read_b128 v[2:5], v187 offset:6912
	ds_read_b128 v[6:9], v187 offset:6976
	s_waitcnt lgkmcnt(1)
	v_mfma_f32_16x16x32_bf16 v[2:5], v[2:5], v[66:69], 0
	s_waitcnt lgkmcnt(0)
	v_mfma_f32_16x16x32_bf16 v[46:49], v[6:9], v[70:73], v[2:5]
.LBB0_291:
	s_or_b64 exec, exec, s[0:1]
	v_cmp_gt_u32_e64 s[40:41], 5, v1
	v_mov_b32_e32 v30, 0
	s_and_saveexec_b64 s[0:1], s[40:41]
	s_cbranch_execz .Lz_4
	ds_read_b128 v[2:5], v187 offset:9216
	ds_read_b128 v[6:9], v187 offset:9280
	s_waitcnt lgkmcnt(1)
	v_mfma_f32_16x16x32_bf16 v[2:5], v[2:5], v[66:69], 0
	s_waitcnt lgkmcnt(0)
	v_mfma_f32_16x16x32_bf16 v[50:53], v[6:9], v[70:73], v[2:5]
.LBB0_293:
	s_or_b64 exec, exec, s[0:1]
	v_cmp_gt_u32_e64 s[24:25], 6, v1
	s_and_saveexec_b64 s[0:1], s[24:25]
	s_cbranch_execz .Lz_5
	ds_read_b128 v[2:5], v187 offset:11520
	ds_read_b128 v[6:9], v187 offset:11584
	s_waitcnt lgkmcnt(1)
	v_mfma_f32_16x16x32_bf16 v[2:5], v[2:5], v[66:69], 0
	s_waitcnt lgkmcnt(0)
	v_mfma_f32_16x16x32_bf16 v[30:33], v[6:9], v[70:73], v[2:5]

; __device__ __forceinline__ void swa_prompt_unit(const Args& a, unsigned char* lds, int unit, int tid) {
;     ...
;         for (int t = 0; t < 16; ++t) { sc[t] = (f32x4){0.f, 0.f, 0.f, 0.f};
;             if (t >= t0 && t <= t0 + 8) {
; #pragma unroll
;                 for (int kk = 0; kk < 2; ++kk) { const bf16x8 af = *(const bf16x8*)(KL + (t * 16 + r16) * 144 + kk * 64 + q4 * 16); sc[t] = __builtin_amdgcn_mfma_f32_16x16x32_bf16(af, qf[kk], sc[t], 0, 0, 0); } } }
.LBB0_297:
	s_andn2_saveexec_b64 s[0:1], s[0:1]
	s_nop 6
	v_mov_b32_e32 v34, 0
	v_mov_b32_e32 v35, 0
	v_mov_b32_e32 v36, 0
	v_mov_b32_e32 v37, 0
	s_or_b64 exec, exec, s[0:1]
	ds_read_b128 v[2:5], v187 offset:16128
	ds_read_b128 v[6:9], v187 offset:16192
	v_mov_b32_e32 v10, 0
	s_waitcnt lgkmcnt(1)
	v_mfma_f32_16x16x32_bf16 v[2:5], v[2:5], v[66:69], 0
	s_waitcnt lgkmcnt(0)
	v_mfma_f32_16x16x32_bf16 v[42:45], v[6:9], v[70:73], v[2:5]
	ds_read_b128 v[6:9], v187 offset:18496
	s_nop 4
	ds_read_b128 v[2:5], v187 offset:18432
	s_waitcnt lgkmcnt(0)
	v_mfma_f32_16x16x32_bf16 v[2:5], v[2:5], v[66:69], 0
	v_mfma_f32_16x16x32_bf16 v[38:41], v[6:9], v[70:73], v[2:5]
	s_and_saveexec_b64 s[0:1], vcc
	s_cbranch_execz .Lz_6
	s_nop 4
	ds_read_b128 v[2:5], v187 offset:20736
	ds_read_b128 v[6:9], v187 offset:20800
	s_waitcnt lgkmcnt(1)
	v_mfma_f32_16x16x32_bf16 v[2:5], v[2:5], v[66:69], 0
	s_waitcnt lgkmcnt(0)
	v_mfma_f32_16x16x32_bf16 v[26:29], v[6:9], v[70:73], v[2:5]
.LBB0_301:
	s_or_b64 exec, exec, s[0:1]
	v_add_u32_e32 v1, 8, v1
	v_cmp_lt_u32_e64 s[22:23], 9, v1
	s_and_saveexec_b64 s[0:1], s[22:23]
	s_cbranch_execz .Lz_7
	ds_read_b128 v[2:5], v187 offset:23040
	ds_read_b128 v[6:9], v187 offset:23104
	s_waitcnt lgkmcnt(1)
	v_mfma_f32_16x16x32_bf16 v[2:5], v[2:5], v[66:69], 0
	s_waitcnt lgkmcnt(0)
	v_mfma_f32_16x16x32_bf16 v[22:25], v[6:9], v[70:73], v[2:5]
.LBB0_303:
	s_or_b64 exec, exec, s[0:1]
	v_cmp_lt_u32_e64 s[36:37], 10, v1
	s_and_saveexec_b64 s[0:1], s[36:37]
	s_cbranch_execz .Lz_8
	ds_read_b128 v[2:5], v187 offset:25344
	ds_read_b128 v[6:9], v187 offset:25408
	s_waitcnt lgkmcnt(1)
	v_mfma_f32_16x16x32_bf16 v[2:5], v[2:5], v[66:69], 0
	s_waitcnt lgkmcnt(0)
	v_mfma_f32_16x16x32_bf16 v[10:13], v[6:9], v[70:73], v[2:5]
.LBB0_305:
	s_or_b64 exec, exec, s[0:1]
	v_cmp_lt_u32_e64 s[20:21], 11, v1
	v_mov_b32_e32 v6, 0
	s_and_saveexec_b64 s[0:1], s[20:21]
	s_cbranch_execz .Lz_9
	ds_read_b128 v[2:5], v187 offset:27648
	ds_read_b128 v[14:17], v187 offset:27712
	s_waitcnt lgkmcnt(1)
	v_mfma_f32_16x16x32_bf16 v[2:5], v[2:5], v[66:69], 0
	s_waitcnt lgkmcnt(0)
	v_mfma_f32_16x16x32_bf16 v[18:21], v[14:17], v[70:73], v[2:5]
.LBB0_307:
	s_or_b64 exec, exec, s[0:1]
	v_cmp_lt_u32_e64 s[34:35], 12, v1
	s_and_saveexec_b64 s[0:1], s[34:35]
	s_cbranch_execz .Lz_10
	ds_read_b128 v[2:5], v187 offset:29952
	ds_read_b128 v[6:9], v187 offset:30016
	s_waitcnt lgkmcnt(1)
	v_mfma_f32_16x16x32_bf16 v[2:5], v[2:5], v[66:69], 0
	s_waitcnt lgkmcnt(0)
	v_mfma_f32_16x16x32_bf16 v[6:9], v[6:9], v[70:73], v[2:5]
.LBB0_309:
	s_or_b64 exec, exec, s[0:1]
	v_cmp_lt_u32_e64 s[18:19], 13, v1
	s_nop 3
	v_mov_b32_e32 v2, 0
	s_and_saveexec_b64 s[0:1], s[18:19]
	s_cbranch_execz .Lz_11
	ds_read_b128 v[14:17], v187 offset:32256
	ds_read_b128 v[192:195], v187 offset:32320
	s_waitcnt lgkmcnt(1)
	v_mfma_f32_16x16x32_bf16 v[14:17], v[14:17], v[66:69], 0
	s_waitcnt lgkmcnt(0)
	v_mfma_f32_16x16x32_bf16 v[14:17], v[192:195], v[70:73], v[14:17]

; __device__ __forceinline__ void swa_prompt_unit(const Args& a, unsigned char* lds, int unit, int tid) {
;     ...
;         mx = fmaxf(mx, __shfl_xor(mx, 16)); mx = fmaxf(mx, __shfl_xor(mx, 32)); mx = fmaxf(mx, sk);
;         float sum = 0.f;
; #pragma unroll
;         for (int t = 0; t < 16; ++t) { if (t >= t0 && t <= t0 + 8) {
; #pragma unroll
;             for (int j = 0; j < 4; ++j) { const int key = t * 16 + q4 * 4 + j; const bool ok = key > qi && key <= qi + 128 && (blk > 0 || key >= 128); const float p = ok ? __expf(sc[t][j] - mx) : 0.f; sc[t][j] = p; sum += p; } }
;             else sc[t] = (f32x4){0.f, 0.f, 0.f, 0.f}; }
.LBB0_328:
	s_or_b64 exec, exec, s[96:97]
	v_and_b32_e32 v66, 64, v151
	v_xor_b32_e32 v68, 16, v151
	v_add_u32_e32 v66, 64, v66
	v_cmp_lt_i32_e64 s[0:1], v68, v66
	v_xor_b32_e32 v69, 32, v151
	v_mov_b32_e32 v73, 0
	v_cndmask_b32_e64 v68, v151, v68, s[0:1]
	v_lshlrev_b32_e32 v85, 2, v68
	ds_bpermute_b32 v68, v85, v67
	v_max_f32_e32 v67, v67, v67
	v_cmp_lt_i32_e64 s[0:1], v69, v66
	s_waitcnt lgkmcnt(0)
	v_max_f32_e32 v68, v68, v68
	v_max_f32_e32 v68, v67, v68
	v_cndmask_b32_e64 v67, v151, v69, s[0:1]
	v_lshlrev_b32_e32 v128, 2, v67
	ds_bpermute_b32 v69, v128, v68
	v_mov_b32_e32 v67, 0
	s_waitcnt lgkmcnt(0)
	v_max3_f32 v72, v68, v69, v95
	s_and_saveexec_b64 s[96:97], s[44:45]
	s_cbranch_execz .Lz_12
	v_sub_f32_e32 v62, v62, v72
	v_mul_f32_e32 v62, 0x3fb8aa3b, v62
	v_exp_f32_e32 v62, v62
	v_sub_f32_e32 v63, v63, v72
	v_mul_f32_e32 v63, 0x3fb8aa3b, v63
	s_and_b64 s[0:1], s[16:17], s[52:53]
	v_cndmask_b32_e64 v68, 0, v62, s[0:1]
	v_exp_f32_e32 v62, v63
	v_cmp_ge_u32_e64 s[0:1], v108, v191
	s_and_b64 s[0:1], s[16:17], s[0:1]
	v_add_f32_e32 v63, 0, v68
	v_cndmask_b32_e64 v69, 0, v62, s[0:1]
	v_sub_f32_e32 v62, v64, v72
	v_mul_f32_e32 v62, 0x3fb8aa3b, v62
	v_exp_f32_e32 v62, v62
	v_cmp_gt_u32_e64 s[0:1], v109, v191
	s_and_b64 s[0:1], s[16:17], s[0:1]
	v_add_f32_e32 v63, v69, v63
	v_cndmask_b32_e64 v70, 0, v62, s[0:1]
	v_sub_f32_e32 v62, v65, v72
	v_mul_f32_e32 v62, 0x3fb8aa3b, v62
	v_exp_f32_e32 v62, v62
	v_cmp_gt_u32_e64 s[0:1], v110, v191
	s_and_b64 s[0:1], s[16:17], s[0:1]
	v_add_f32_e32 v63, v70, v63
	v_cndmask_b32_e64 v71, 0, v62, s[0:1]
	v_add_f32_e32 v73, v71, v63
.LBB0_330:
	s_or_b64 exec, exec, s[96:97]
	s_and_saveexec_b64 s[44:45], s[28:29]
	s_cbranch_execz .Lz_13
	v_sub_f32_e32 v54, v54, v72
	v_mul_f32_e32 v54, 0x3fb8aa3b, v54
	v_exp_f32_e32 v54, v54
	v_cmp_gt_u32_e64 s[0:1], v111, v191
	v_sub_f32_e32 v55, v55, v72
	s_and_b64 s[0:1], s[16:17], s[0:1]
	v_cndmask_b32_e64 v67, 0, v54, s[0:1]
	v_mul_f32_e32 v54, 0x3fb8aa3b, v55
	v_exp_f32_e32 v54, v54
	v_cmp_gt_u32_e64 s[0:1], v112, v191
	s_and_b64 s[0:1], s[16:17], s[0:1]
	v_add_f32_e32 v55, v67, v73
	v_cndmask_b32_e64 v62, 0, v54, s[0:1]
	v_sub_f32_e32 v54, v56, v72
	v_mul_f32_e32 v54, 0x3fb8aa3b, v54
	v_exp_f32_e32 v54, v54
	v_cmp_gt_u32_e64 s[0:1], v113, v191
	s_and_b64 s[0:1], s[16:17], s[0:1]
	v_add_f32_e32 v55, v62, v55
	v_cndmask_b32_e64 v63, 0, v54, s[0:1]
	v_sub_f32_e32 v54, v57, v72
	v_mul_f32_e32 v54, 0x3fb8aa3b, v54
	v_exp_f32_e32 v54, v54
	v_cmp_gt_u32_e64 s[0:1], v114, v191
	s_and_b64 s[0:1], s[16:17], s[0:1]
	v_add_f32_e32 v55, v63, v55
	v_cndmask_b32_e64 v65, 0, v54, s[0:1]
	v_add_f32_e32 v73, v65, v55
.LBB0_332:
	s_or_b64 exec, exec, s[44:45]
	v_mov_b32_e32 v54, 0
	s_and_saveexec_b64 s[44:45], s[42:43]
	s_cbranch_execz .Lz_14
	v_sub_f32_e32 v55, v58, v72
	v_mul_f32_e32 v55, 0x3fb8aa3b, v55
	v_exp_f32_e32 v55, v55
	v_sub_f32_e32 v56, v59, v72
	v_mul_f32_e32 v56, 0x3fb8aa3b, v56
	v_cmp_gt_u32_e64 s[0:1], v115, v191
	v_exp_f32_e32 v56, v56
	v_sub_f32_e32 v58, v60, v72
	s_and_b64 s[0:1], s[16:17], s[0:1]
	v_mul_f32_e32 v58, 0x3fb8aa3b, v58
	v_cndmask_b32_e64 v55, 0, v55, s[0:1]
	v_cmp_gt_u32_e64 s[0:1], v116, v191
	v_exp_f32_e32 v58, v58
	s_and_b64 s[0:1], s[16:17], s[0:1]
	v_cndmask_b32_e64 v56, 0, v56, s[0:1]
	v_cmp_gt_u32_e64 s[0:1], v117, v191
	v_add_f32_e32 v57, v55, v73
	s_and_b64 s[0:1], s[16:17], s[0:1]
	v_add_f32_e32 v59, v56, v57
	v_cndmask_b32_e64 v57, 0, v58, s[0:1]
	v_sub_f32_e32 v58, v61, v72
	v_mul_f32_e32 v58, 0x3fb8aa3b, v58
	v_exp_f32_e32 v58, v58
	v_cmp_gt_u32_e64 s[0:1], v118, v191
	s_and_b64 s[0:1], s[16:17], s[0:1]
	v_add_f32_e32 v59, v57, v59
	v_cndmask_b32_e64 v64, 0, v58, s[0:1]
	v_add_f32_e32 v73, v64, v59
.LBB0_334:
	s_or_b64 exec, exec, s[44:45]
	s_and_saveexec_b64 s[42:43], s[26:27]
	s_cbranch_execz .Lz_15
	v_sub_f32_e32 v46, v46, v72
	v_mul_f32_e32 v46, 0x3fb8aa3b, v46
	v_exp_f32_e32 v46, v46
	v_cmp_gt_u32_e64 s[0:1], v119, v191
	v_sub_f32_e32 v47, v47, v72
	s_and_b64 s[0:1], s[16:17], s[0:1]
	v_cndmask_b32_e64 v54, 0, v46, s[0:1]
	v_mul_f32_e32 v46, 0x3fb8aa3b, v47
	v_exp_f32_e32 v46, v46
	v_cmp_gt_u32_e64 s[0:1], v120, v191
	s_and_b64 s[0:1], s[16:17], s[0:1]
	v_add_f32_e32 v47, v54, v73
	v_cndmask_b32_e64 v58, 0, v46, s[0:1]
	v_sub_f32_e32 v46, v48, v72
	v_mul_f32_e32 v46, 0x3fb8aa3b, v46
	v_exp_f32_e32 v46, v46
	v_cmp_gt_u32_e64 s[0:1], v121, v191
	s_and_b64 s[0:1], s[16:17], s[0:1]
	v_add_f32_e32 v47, v58, v47
	v_cndmask_b32_e64 v59, 0, v46, s[0:1]
	v_sub_f32_e32 v46, v49, v72
	v_mul_f32_e32 v46, 0x3fb8aa3b, v46
	v_exp_f32_e32 v46, v46
	v_cmp_gt_u32_e64 s[0:1], v122, v191
	s_and_b64 s[0:1], s[16:17], s[0:1]
	v_add_f32_e32 v47, v59, v47
	v_cndmask_b32_e64 v61, 0, v46, s[0:1]
	v_add_f32_e32 v73, v61, v47
.LBB0_336:
	s_or_b64 exec, exec, s[42:43]
	v_mov_b32_e32 v46, 0
	s_and_saveexec_b64 s[42:43], s[40:41]
	s_cbranch_execz .Lz_16
	v_sub_f32_e32 v47, v50, v72
	v_mul_f32_e32 v47, 0x3fb8aa3b, v47
	v_exp_f32_e32 v47, v47
	v_sub_f32_e32 v48, v51, v72
	v_mul_f32_e32 v48, 0x3fb8aa3b, v48
	v_cmp_gt_u32_e64 s[0:1], v123, v191
	v_exp_f32_e32 v48, v48
	v_sub_f32_e32 v50, v52, v72
	s_and_b64 s[0:1], s[16:17], s[0:1]
	v_mul_f32_e32 v50, 0x3fb8aa3b, v50
	v_cndmask_b32_e64 v47, 0, v47, s[0:1]
	v_cmp_gt_u32_e64 s[0:1], v129, v191
	v_exp_f32_e32 v50, v50
	s_and_b64 s[0:1], s[16:17], s[0:1]
	v_cndmask_b32_e64 v48, 0, v48, s[0:1]
	v_cmp_gt_u32_e64 s[0:1], v130, v191
	v_add_f32_e32 v49, v47, v73
	s_and_b64 s[0:1], s[16:17], s[0:1]
	v_add_f32_e32 v51, v48, v49
	v_cndmask_b32_e64 v49, 0, v50, s[0:1]
	v_sub_f32_e32 v50, v53, v72
	v_mul_f32_e32 v50, 0x3fb8aa3b, v50
	v_exp_f32_e32 v50, v50
	v_cmp_gt_u32_e64 s[0:1], v131, v191
	s_and_b64 s[0:1], s[16:17], s[0:1]
	v_add_f32_e32 v51, v49, v51
	v_cndmask_b32_e64 v60, 0, v50, s[0:1]
	v_add_f32_e32 v73, v60, v51
; __device__ __forceinline__ void swa_prompt_unit(const Args& a, unsigned char* lds, int unit, int tid) {
;     ...
;         for (int t = 0; t < 16; ++t) { if (t >= t0 && t <= t0 + 8) {
; #pragma unroll
;             for (int j = 0; j < 4; ++j) { const int key = t * 16 + q4 * 4 + j; const bool ok = key > qi && key <= qi + 128 && (blk > 0 || key >= 128); const float p = ok ? __expf(sc[t][j] - mx) : 0.f; sc[t][j] = p; sum += p; } }
;             else sc[t] = (f32x4){0.f, 0.f, 0.f, 0.f}; }
.LBB0_338:
	s_or_b64 exec, exec, s[42:43]
	s_and_saveexec_b64 s[40:41], s[24:25]
	s_cbranch_execz .Lz_17
	v_sub_f32_e32 v30, v30, v72
	v_mul_f32_e32 v30, 0x3fb8aa3b, v30
	v_exp_f32_e32 v30, v30
	v_cmp_gt_u32_e64 s[0:1], v132, v191
	v_sub_f32_e32 v31, v31, v72
	s_and_b64 s[0:1], s[16:17], s[0:1]
	v_cndmask_b32_e64 v46, 0, v30, s[0:1]
	v_mul_f32_e32 v30, 0x3fb8aa3b, v31
	v_exp_f32_e32 v30, v30
	v_cmp_gt_u32_e64 s[0:1], v133, v191
	s_and_b64 s[0:1], s[16:17], s[0:1]
	v_add_f32_e32 v31, v46, v73
	v_cndmask_b32_e64 v50, 0, v30, s[0:1]
	v_sub_f32_e32 v30, v32, v72
	v_mul_f32_e32 v30, 0x3fb8aa3b, v30
	v_exp_f32_e32 v30, v30
	v_cmp_gt_u32_e64 s[0:1], v134, v191
	s_and_b64 s[0:1], s[16:17], s[0:1]
	v_add_f32_e32 v31, v50, v31
	v_cndmask_b32_e64 v51, 0, v30, s[0:1]
	v_sub_f32_e32 v30, v33, v72
	v_mul_f32_e32 v30, 0x3fb8aa3b, v30
	v_exp_f32_e32 v30, v30
	v_cmp_gt_u32_e64 s[0:1], v135, v191
	s_and_b64 s[0:1], s[16:17], s[0:1]
	v_add_f32_e32 v31, v51, v31
	v_cndmask_b32_e64 v52, 0, v30, s[0:1]
	v_add_f32_e32 v73, v52, v31
.LBB0_340:
	s_or_b64 exec, exec, s[40:41]
	v_mov_b32_e32 v30, 0
	s_and_saveexec_b64 s[40:41], s[38:39]
	s_cbranch_execz .Lz_18
	v_sub_f32_e32 v31, v34, v72
	v_mul_f32_e32 v31, 0x3fb8aa3b, v31
	v_exp_f32_e32 v31, v31
	v_sub_f32_e32 v32, v35, v72
	v_mul_f32_e32 v32, 0x3fb8aa3b, v32
	v_cmp_gt_u32_e64 s[0:1], v136, v191
	v_exp_f32_e32 v32, v32
	v_sub_f32_e32 v34, v36, v72
	s_and_b64 s[0:1], s[16:17], s[0:1]
	v_mul_f32_e32 v34, 0x3fb8aa3b, v34
	v_cndmask_b32_e64 v31, 0, v31, s[0:1]
	v_cmp_gt_u32_e64 s[0:1], v137, v191
	v_exp_f32_e32 v34, v34
	s_and_b64 s[0:1], s[16:17], s[0:1]
	v_cndmask_b32_e64 v32, 0, v32, s[0:1]
	v_cmp_gt_u32_e64 s[0:1], v138, v191
	v_add_f32_e32 v33, v31, v73
	s_and_b64 s[0:1], s[16:17], s[0:1]
	v_add_f32_e32 v35, v32, v33
	v_cndmask_b32_e64 v33, 0, v34, s[0:1]
	v_sub_f32_e32 v34, v37, v72
	v_mul_f32_e32 v34, 0x3fb8aa3b, v34
	v_exp_f32_e32 v34, v34
	v_cmp_gt_u32_e64 s[0:1], v139, v191
	s_and_b64 s[0:1], s[16:17], s[0:1]
	v_add_f32_e32 v35, v33, v35
	v_cndmask_b32_e64 v53, 0, v34, s[0:1]
	v_add_f32_e32 v73, v53, v35
.LBB0_342:
	s_or_b64 exec, exec, s[40:41]
	v_sub_f32_e32 v35, v43, v72
	v_mul_f32_e32 v35, 0x3fb8aa3b, v35
	v_exp_f32_e32 v35, v35
	v_sub_f32_e32 v36, v45, v72
	v_mul_f32_e32 v36, 0x3fb8aa3b, v36
	v_sub_f32_e32 v34, v42, v72
	v_cndmask_b32_e64 v43, 0, v35, s[56:57]
	v_sub_f32_e32 v35, v44, v72
	v_mul_f32_e32 v35, 0x3fb8aa3b, v35
	v_exp_f32_e32 v35, v35
	v_exp_f32_e32 v36, v36
	v_mul_f32_e32 v34, 0x3fb8aa3b, v34
	v_exp_f32_e32 v34, v34
	v_cndmask_b32_e64 v44, 0, v35, s[50:51]
	v_cndmask_b32_e64 v45, 0, v36, s[60:61]
	v_sub_f32_e32 v35, v38, v72
	v_sub_f32_e32 v36, v39, v72
	v_mul_f32_e32 v35, 0x3fb8aa3b, v35
	v_mul_f32_e32 v36, 0x3fb8aa3b, v36
	v_cndmask_b32_e64 v42, 0, v34, s[46:47]
	v_exp_f32_e32 v35, v35
	v_exp_f32_e32 v36, v36
	v_add_f32_e32 v34, v42, v73
	v_add_f32_e32 v34, v43, v34
	v_add_f32_e32 v34, v44, v34
	v_add_f32_e32 v37, v45, v34
	v_cndmask_b32_e64 v34, v35, 0, s[52:53]
	v_cndmask_b32_e64 v35, v36, 0, s[58:59]
	v_sub_f32_e32 v36, v40, v72
	v_mul_f32_e32 v36, 0x3fb8aa3b, v36
	v_sub_f32_e32 v38, v41, v72
	v_exp_f32_e32 v36, v36
	v_mul_f32_e32 v38, 0x3fb8aa3b, v38
	v_exp_f32_e32 v38, v38
	v_add_f32_e32 v37, v34, v37
	v_add_f32_e32 v37, v35, v37
	v_cndmask_b32_e64 v36, v36, 0, s[48:49]
	v_add_f32_e32 v39, v36, v37
	v_cndmask_b32_e64 v37, v38, 0, s[54:55]
	v_add_f32_e32 v204, v37, v39
	s_and_saveexec_b64 s[0:1], vcc
	s_cbranch_execz .Lz_19
	v_sub_f32_e32 v26, v26, v72
	v_mul_f32_e32 v26, 0x3fb8aa3b, v26
	v_sub_f32_e32 v27, v27, v72
	v_exp_f32_e32 v26, v26
	v_mul_f32_e32 v27, 0x3fb8aa3b, v27
	v_exp_f32_e32 v27, v27
	v_cmp_le_u32_e32 vcc, v147, v1
	s_nop 1
	v_cndmask_b32_e32 v30, 0, v26, vcc
	v_cmp_le_u32_e32 vcc, v149, v1
	v_add_f32_e32 v26, v30, v204
	s_nop 0
	v_cndmask_b32_e32 v38, 0, v27, vcc
	v_sub_f32_e32 v27, v28, v72
	v_mul_f32_e32 v27, 0x3fb8aa3b, v27
	v_sub_f32_e32 v28, v29, v72
	v_exp_f32_e32 v27, v27
	v_mul_f32_e32 v28, 0x3fb8aa3b, v28
	v_exp_f32_e32 v28, v28
	v_cmp_le_u32_e32 vcc, v150, v1
	v_add_f32_e32 v26, v38, v26
	s_nop 0
	v_cndmask_b32_e32 v39, 0, v27, vcc
	v_cmp_le_u32_e32 vcc, v152, v1
	v_add_f32_e32 v26, v39, v26
	s_nop 0
	v_cndmask_b32_e32 v40, 0, v28, vcc
	v_add_f32_e32 v204, v40, v26
.LBB0_344:
	s_or_b64 exec, exec, s[0:1]
	v_mov_b32_e32 v26, 0
	s_and_saveexec_b64 s[0:1], s[22:23]
	s_cbranch_execz .Lz_20
	v_sub_f32_e32 v22, v22, v72
	v_mul_f32_e32 v22, 0x3fb8aa3b, v22
	v_sub_f32_e32 v23, v23, v72
	v_exp_f32_e32 v22, v22
	v_mul_f32_e32 v23, 0x3fb8aa3b, v23
	v_exp_f32_e32 v23, v23
	v_cmp_le_u32_e32 vcc, v153, v1
	s_nop 1
	v_cndmask_b32_e32 v27, 0, v22, vcc
	v_cmp_le_u32_e32 vcc, v154, v1
	v_add_f32_e32 v22, v27, v204
	s_nop 0
	v_cndmask_b32_e32 v28, 0, v23, vcc
	v_sub_f32_e32 v23, v24, v72
	v_mul_f32_e32 v23, 0x3fb8aa3b, v23
	v_sub_f32_e32 v24, v25, v72
	v_exp_f32_e32 v23, v23
	v_mul_f32_e32 v24, 0x3fb8aa3b, v24
	v_exp_f32_e32 v24, v24
	v_cmp_le_u32_e32 vcc, v155, v1
	v_add_f32_e32 v22, v28, v22
	s_nop 0
	v_cndmask_b32_e32 v29, 0, v23, vcc
	v_cmp_le_u32_e32 vcc, v156, v1
	v_add_f32_e32 v22, v29, v22
	s_nop 0
	v_cndmask_b32_e32 v41, 0, v24, vcc
	v_add_f32_e32 v204, v41, v22
; __device__ __forceinline__ void swa_prompt_unit(const Args& a, unsigned char* lds, int unit, int tid) {
;     ...
;         for (int t = 0; t < 16; ++t) { if (t >= t0 && t <= t0 + 8) {
; #pragma unroll
;             for (int j = 0; j < 4; ++j) { const int key = t * 16 + q4 * 4 + j; const bool ok = key > qi && key <= qi + 128 && (blk > 0 || key >= 128); const float p = ok ? __expf(sc[t][j] - mx) : 0.f; sc[t][j] = p; sum += p; } }
;             else sc[t] = (f32x4){0.f, 0.f, 0.f, 0.f}; }
.LBB0_346:
	s_or_b64 exec, exec, s[0:1]
	s_and_saveexec_b64 s[0:1], s[36:37]
	s_cbranch_execz .Lz_21
	v_sub_f32_e32 v10, v10, v72
	v_mul_f32_e32 v10, 0x3fb8aa3b, v10
	v_sub_f32_e32 v11, v11, v72
	v_exp_f32_e32 v10, v10
	v_mul_f32_e32 v11, 0x3fb8aa3b, v11
	v_exp_f32_e32 v11, v11
	v_cmp_le_u32_e32 vcc, v157, v1
	s_nop 1
	v_cndmask_b32_e32 v26, 0, v10, vcc
	v_cmp_le_u32_e32 vcc, v158, v1
	v_add_f32_e32 v10, v26, v204
	s_nop 0
	v_cndmask_b32_e32 v25, 0, v11, vcc
	v_sub_f32_e32 v11, v12, v72
	v_mul_f32_e32 v11, 0x3fb8aa3b, v11
	v_sub_f32_e32 v12, v13, v72
	v_exp_f32_e32 v11, v11
	v_mul_f32_e32 v12, 0x3fb8aa3b, v12
	v_exp_f32_e32 v12, v12
	v_cmp_le_u32_e32 vcc, v159, v1
	v_add_f32_e32 v10, v25, v10
	s_nop 0
	v_cndmask_b32_e32 v193, 0, v11, vcc
	v_cmp_le_u32_e32 vcc, v160, v1
	v_add_f32_e32 v10, v193, v10
	s_nop 0
	v_cndmask_b32_e32 v194, 0, v12, vcc
	v_add_f32_e32 v204, v194, v10
.LBB0_348:
	s_or_b64 exec, exec, s[0:1]
	v_mov_b32_e32 v22, 0
	s_and_saveexec_b64 s[0:1], s[20:21]
	s_cbranch_execz .Lz_22
	v_sub_f32_e32 v10, v18, v72
	v_mul_f32_e32 v10, 0x3fb8aa3b, v10
	v_sub_f32_e32 v11, v19, v72
	v_exp_f32_e32 v10, v10
	v_mul_f32_e32 v11, 0x3fb8aa3b, v11
	v_exp_f32_e32 v11, v11
	v_cmp_le_u32_e32 vcc, v161, v1
	v_sub_f32_e32 v12, v21, v72
	v_mul_f32_e32 v12, 0x3fb8aa3b, v12
	v_cndmask_b32_e32 v23, 0, v10, vcc
	v_cmp_le_u32_e32 vcc, v162, v1
	v_exp_f32_e32 v12, v12
	v_add_f32_e32 v10, v23, v204
	v_cndmask_b32_e32 v24, 0, v11, vcc
	v_sub_f32_e32 v11, v20, v72
	v_mul_f32_e32 v11, 0x3fb8aa3b, v11
	v_exp_f32_e32 v11, v11
	v_cmp_le_u32_e32 vcc, v163, v1
	v_add_f32_e32 v10, v24, v10
	s_nop 0
	v_cndmask_b32_e32 v73, 0, v11, vcc
	v_cmp_le_u32_e32 vcc, v164, v1
	v_add_f32_e32 v10, v73, v10
	s_nop 0
	v_cndmask_b32_e32 v192, 0, v12, vcc
	v_add_f32_e32 v204, v192, v10
.LBB0_350:
	s_or_b64 exec, exec, s[0:1]
	s_and_saveexec_b64 s[0:1], s[34:35]
	s_cbranch_execz .Lz_23
	v_sub_f32_e32 v6, v6, v72
	v_mul_f32_e32 v6, 0x3fb8aa3b, v6
	v_sub_f32_e32 v7, v7, v72
	v_exp_f32_e32 v6, v6
	v_mul_f32_e32 v7, 0x3fb8aa3b, v7
	v_exp_f32_e32 v7, v7
	v_cmp_le_u32_e32 vcc, v165, v1
	s_nop 1
	v_cndmask_b32_e32 v22, 0, v6, vcc
	v_cmp_le_u32_e32 vcc, v166, v1
	v_add_f32_e32 v6, v22, v204
	s_nop 0
	v_cndmask_b32_e32 v196, 0, v7, vcc
	v_sub_f32_e32 v7, v8, v72
	v_mul_f32_e32 v7, 0x3fb8aa3b, v7
	v_sub_f32_e32 v8, v9, v72
	v_exp_f32_e32 v7, v7
	v_mul_f32_e32 v8, 0x3fb8aa3b, v8
	v_exp_f32_e32 v8, v8
	v_cmp_le_u32_e32 vcc, v167, v1
	v_add_f32_e32 v6, v196, v6
	s_nop 0
	v_cndmask_b32_e32 v199, 0, v7, vcc
	v_cmp_le_u32_e32 vcc, v168, v1
	v_add_f32_e32 v6, v199, v6
	s_nop 0
	v_cndmask_b32_e32 v200, 0, v8, vcc
	v_add_f32_e32 v204, v200, v6
.LBB0_352:
	s_or_b64 exec, exec, s[0:1]
	v_mov_b32_e32 v20, 0
	s_and_saveexec_b64 s[0:1], s[18:19]
	s_cbranch_execz .Lz_24
	v_sub_f32_e32 v6, v14, v72
	v_mul_f32_e32 v6, 0x3fb8aa3b, v6
	v_sub_f32_e32 v7, v15, v72
	v_exp_f32_e32 v6, v6
	v_mul_f32_e32 v7, 0x3fb8aa3b, v7
	v_exp_f32_e32 v7, v7
	v_cmp_le_u32_e32 vcc, v169, v1
	v_sub_f32_e32 v8, v17, v72
	v_mul_f32_e32 v8, 0x3fb8aa3b, v8
	v_cndmask_b32_e32 v21, 0, v6, vcc
	v_cmp_le_u32_e32 vcc, v170, v1
	v_exp_f32_e32 v8, v8
	v_add_f32_e32 v6, v21, v204
	v_cndmask_b32_e32 v195, 0, v7, vcc
	v_sub_f32_e32 v7, v16, v72
	v_mul_f32_e32 v7, 0x3fb8aa3b, v7
	v_exp_f32_e32 v7, v7
	v_cmp_le_u32_e32 vcc, v171, v1
	v_add_f32_e32 v6, v195, v6
	s_nop 0
	v_cndmask_b32_e32 v197, 0, v7, vcc
	v_cmp_le_u32_e32 vcc, v172, v1
	v_add_f32_e32 v6, v197, v6
	s_nop 0
	v_cndmask_b32_e32 v198, 0, v8, vcc
	v_add_f32_e32 v204, v198, v6
.LBB0_354:
	s_or_b64 exec, exec, s[0:1]
	s_and_saveexec_b64 s[0:1], s[30:31]
	s_cbranch_execz .Lz_25
	v_sub_f32_e32 v2, v2, v72
	v_mul_f32_e32 v2, 0x3fb8aa3b, v2
	v_sub_f32_e32 v3, v3, v72
	v_exp_f32_e32 v2, v2
	v_mul_f32_e32 v3, 0x3fb8aa3b, v3
	v_exp_f32_e32 v3, v3
	v_cmp_le_u32_e32 vcc, v173, v1
	s_nop 1
	v_cndmask_b32_e32 v20, 0, v2, vcc
	v_cmp_le_u32_e32 vcc, v174, v1
	v_add_f32_e32 v2, v20, v204
	s_nop 0
	v_cndmask_b32_e32 v201, 0, v3, vcc
	v_sub_f32_e32 v3, v4, v72
	v_mul_f32_e32 v3, 0x3fb8aa3b, v3
	v_sub_f32_e32 v4, v5, v72
	v_exp_f32_e32 v3, v3
	v_mul_f32_e32 v4, 0x3fb8aa3b, v4
	v_exp_f32_e32 v4, v4
	v_cmp_le_u32_e32 vcc, v175, v1
	v_add_f32_e32 v2, v201, v2
	s_nop 0
	v_cndmask_b32_e32 v202, 0, v3, vcc
	v_cmp_le_u32_e32 vcc, v176, v1
	v_add_f32_e32 v2, v202, v2
	s_nop 0
	v_cndmask_b32_e32 v203, 0, v4, vcc
	v_add_f32_e32 v204, v203, v2

; __device__ __forceinline__ void swa_prompt_unit(const Args& a, unsigned char* lds, int unit, int tid) {
;     ...
;         for (int t = 0; t < 16; ++t) { sc[t] = (f32x4){0.f, 0.f, 0.f, 0.f};
;             if (t >= t0 && t <= t0 + 8) {
; #pragma unroll
;                 for (int kk = 0; kk < 2; ++kk) { const bf16x8 af = *(const bf16x8*)(KL + (t * 16 + r16) * 144 + kk * 64 + q4 * 16); sc[t] = __builtin_amdgcn_mfma_f32_16x16x32_bf16(af, qf[kk], sc[t], 0, 0, 0); } } }
;         float mx = -3.0e38f;
; #pragma unroll
;         for (int t = 0; t < 16; ++t) if (t >= t0 && t <= t0 + 8) {
; #pragma unroll
;             for (int j = 0; j < 4; ++j) { const int key = t * 16 + q4 * 4 + j; const bool ok = key > qi && key <= qi + 128 && (blk > 0 || key >= 128); if (ok) mx = fmaxf(mx, sc[t][j]); } }
;         mx = fmaxf(mx, __shfl_xor(mx, 16)); mx = fmaxf(mx, __shfl_xor(mx, 32)); mx = fmaxf(mx, sk);
;         float sum = 0.f;
; #pragma unroll
;         for (int t = 0; t < 16; ++t) { if (t >= t0 && t <= t0 + 8) {
; #pragma unroll
;             for (int j = 0; j < 4; ++j) { const int key = t * 16 + q4 * 4 + j; const bool ok = key > qi && key <= qi + 128 && (blk > 0 || key >= 128); const float p = ok ? __expf(sc[t][j] - mx) : 0.f; sc[t][j] = p; sum += p; } }
;             else sc[t] = (f32x4){0.f, 0.f, 0.f, 0.f}; }
.Lz_1:
	s_or_b64 exec, exec, s[0:1]
	v_mov_b32_e32 v55, 0
	v_mov_b32_e32 v56, 0
	v_mov_b32_e32 v57, 0
	s_branch .LBB0_287
.Lz_2:
	s_or_b64 exec, exec, s[0:1]
	v_mov_b32_e32 v58, 0
	v_mov_b32_e32 v59, 0
	v_mov_b32_e32 v60, 0
	v_mov_b32_e32 v61, 0
	s_branch .LBB0_289
.Lz_3:
	s_or_b64 exec, exec, s[0:1]
	v_mov_b32_e32 v47, 0
	v_mov_b32_e32 v48, 0
	v_mov_b32_e32 v49, 0
	s_branch .LBB0_291
.Lz_4:
	s_or_b64 exec, exec, s[0:1]
	v_mov_b32_e32 v50, 0
	v_mov_b32_e32 v51, 0
	v_mov_b32_e32 v52, 0
	v_mov_b32_e32 v53, 0
	s_branch .LBB0_293
.Lz_5:
	s_or_b64 exec, exec, s[0:1]
	v_mov_b32_e32 v31, 0
	v_mov_b32_e32 v32, 0
	v_mov_b32_e32 v33, 0
	s_branch .LBB0_295
.Lz_6:
	s_or_b64 exec, exec, s[0:1]
	v_mov_b32_e32 v26, 0
	v_mov_b32_e32 v27, 0
	v_mov_b32_e32 v28, 0
	v_mov_b32_e32 v29, 0
	s_branch .LBB0_301
.Lz_7:
	s_or_b64 exec, exec, s[0:1]
	v_mov_b32_e32 v22, 0
	v_mov_b32_e32 v23, 0
	v_mov_b32_e32 v24, 0
	v_mov_b32_e32 v25, 0
	s_branch .LBB0_303
.Lz_8:
	s_or_b64 exec, exec, s[0:1]
	v_mov_b32_e32 v11, 0
	v_mov_b32_e32 v12, 0
	v_mov_b32_e32 v13, 0
	s_branch .LBB0_305
.Lz_9:
	s_or_b64 exec, exec, s[0:1]
	v_mov_b32_e32 v18, 0
	v_mov_b32_e32 v19, 0
	v_mov_b32_e32 v20, 0
	v_mov_b32_e32 v21, 0
	s_branch .LBB0_307
.Lz_10:
	s_or_b64 exec, exec, s[0:1]
	v_mov_b32_e32 v7, 0
	v_mov_b32_e32 v8, 0
	v_mov_b32_e32 v9, 0
	s_branch .LBB0_309
.Lz_11:
	s_or_b64 exec, exec, s[0:1]
	v_mov_b32_e32 v14, 0
	v_mov_b32_e32 v15, 0
	v_mov_b32_e32 v16, 0
	v_mov_b32_e32 v17, 0
	s_branch .LBB0_311
.Lz_12:
	s_or_b64 exec, exec, s[96:97]
	v_mov_b32_e32 v70, 0
	v_mov_b32_e32 v71, 0
	v_mov_b32_e32 v68, 0
	v_mov_b32_e32 v69, 0
	s_branch .LBB0_330
.Lz_13:
	s_or_b64 exec, exec, s[44:45]
	v_mov_b32_e32 v62, 0
	v_mov_b32_e32 v63, 0
	v_mov_b32_e32 v65, 0
	s_branch .LBB0_332
.Lz_14:
	s_or_b64 exec, exec, s[44:45]
	v_mov_b32_e32 v55, 0
	v_mov_b32_e32 v56, 0
	v_mov_b32_e32 v57, 0
	v_mov_b32_e32 v64, 0
	s_branch .LBB0_334
.Lz_15:
	s_or_b64 exec, exec, s[42:43]
	v_mov_b32_e32 v58, 0
	v_mov_b32_e32 v59, 0
	v_mov_b32_e32 v61, 0
	s_branch .LBB0_336
.Lz_16:
	s_or_b64 exec, exec, s[42:43]
	v_mov_b32_e32 v47, 0
	v_mov_b32_e32 v48, 0
	v_mov_b32_e32 v49, 0
	v_mov_b32_e32 v60, 0
	s_branch .LBB0_338
.Lz_17:
	s_or_b64 exec, exec, s[40:41]
	v_mov_b32_e32 v50, 0
	v_mov_b32_e32 v51, 0
	v_mov_b32_e32 v52, 0
	s_branch .LBB0_340
.Lz_18:
	s_or_b64 exec, exec, s[40:41]
	v_mov_b32_e32 v31, 0
	v_mov_b32_e32 v32, 0
	v_mov_b32_e32 v33, 0
	v_mov_b32_e32 v53, 0
	s_branch .LBB0_342
.Lz_19:
	s_or_b64 exec, exec, s[0:1]
	v_mov_b32_e32 v38, 0
	v_mov_b32_e32 v39, 0
	v_mov_b32_e32 v40, 0
	s_branch .LBB0_344
.Lz_20:
	s_or_b64 exec, exec, s[0:1]
	v_mov_b32_e32 v27, 0
	v_mov_b32_e32 v28, 0
	v_mov_b32_e32 v29, 0
	v_mov_b32_e32 v41, 0
	s_branch .LBB0_346
.Lz_21:
	s_or_b64 exec, exec, s[0:1]
	v_mov_b32_e32 v25, 0
	v_mov_b32_e32 v193, 0
	v_mov_b32_e32 v194, 0
	s_branch .LBB0_348
.Lz_22:
	s_or_b64 exec, exec, s[0:1]
	v_mov_b32_e32 v23, 0
	v_mov_b32_e32 v24, 0
	v_mov_b32_e32 v73, 0
	v_mov_b32_e32 v192, 0
	s_branch .LBB0_350
.Lz_23:
	s_or_b64 exec, exec, s[0:1]
	v_mov_b32_e32 v196, 0
	v_mov_b32_e32 v199, 0
	v_mov_b32_e32 v200, 0
	s_branch .LBB0_352
.Lz_24:
	s_or_b64 exec, exec, s[0:1]
	v_mov_b32_e32 v21, 0
	v_mov_b32_e32 v195, 0
	v_mov_b32_e32 v197, 0
	v_mov_b32_e32 v198, 0
	s_branch .LBB0_354
.Lz_25:
	s_or_b64 exec, exec, s[0:1]
	v_mov_b32_e32 v201, 0
	v_mov_b32_e32 v202, 0
	v_mov_b32_e32 v203, 0
	s_branch .LBB0_356
